# differential attention pass prologues: second key tile loads issued with the first batch instead of after the first QK^T
# speedup vs baseline: 1.0036x; 1.0036x over previous
; __device__ __forceinline__ int v_st(int k, int c) { const int kk = (k & ~0xC) | ((k & 4) << 1) | ((k & 8) >> 1); return ((kk >> 3) * 4 + (c >> 5)) * 512 + ((kk & 7) * 32 + (c & 31)) * 2; }
; __device__ __forceinline__ int v_rd_base(int lane) { return ((lane & 3) << 3) | (((lane >> 2) & 3) << 6) | (((lane >> 4) & 1) << 5) | (((lane >> 5) & 1) << 8); }
; template <int DK, bool QL>
; __device__ __forceinline__ void qkt(f32x16& p0, f32x16& p1, const bf16* Ks, const bf16x8* qr, const char* ql, int r32, int hi) {
;   p0 = f32x16{}; p1 = f32x16{};
; #pragma unroll
;   for (int d0 = 0; d0 < DK / 16; ++d0) { int cb = (d0 * 16 + hi * 8) * 2;
;     const bf16x8 qv = QL ? *reinterpret_cast<const bf16x8*>(ql + d0 * 1024) : qr[d0];
;     bf16x8 b0 = *reinterpret_cast<const bf16x8*>((const char*)Ks + kswz<DK>(r32, cb));
;     bf16x8 b1 = *reinterpret_cast<const bf16x8*>((const char*)Ks + kswz<DK>(32 + r32, cb));
;     p0 = __builtin_amdgcn_mfma_f32_32x32x16_bf16(b0, qv, p0, 0, 0, 0);
;     p1 = __builtin_amdgcn_mfma_f32_32x32x16_bf16(b1, qv, p1, 0, 0, 0); }
; }
; template <int DK, bool NA, bool QL, int SD> ...
;     ...
;   float m_reg = -1e30f, l_reg = 0; bf16x8 qr[QL ? 1 : DK / 16];
;   char* ql = lds + Q_OFF + (wid * (DK / 16) * 64 + lane) * 16;
; #pragma unroll
;   for (int d = 0; d < 4; ++d) o[d] = f32x16{};
;   const bf16* Qw = Qb + (long)(wid * 32 + r32) * LDP + hi * 8;
; #pragma unroll
;   for (int d0 = 0; d0 < DK / 16; ++d0) { const bf16x8 qv = *reinterpret_cast<const bf16x8*>(Qw + d0 * 16); if (QL) *reinterpret_cast<bf16x8*>(ql + d0 * 1024) = qv; else qr[d0] = qv; }
;   const int sr = tid >> 4, sc = (tid & 15) * 8, vst0 = v_st(sr, sc), vst1 = v_st(32 + sr, sc);
;   const int ksr = DK == 128 ? sr : (tid >> 3), ksc = DK == 128 ? sc : (tid & 7) * 8;
;   const int vb0 = (int)(uintptr_t)V_lds + v_rd_base(lane);
;   struct { bf16x8 vs0, vs1, ks0, ks1; } sr_[SD];
;     ...
;   f32x16 pA0, pA1, pB0, pB1; float mnA, mnB, alA, alB; bf16x8 pa0, pa1, pa2, pa3;
;   constexpr int SE = 0, SO = SD - 1;
;   SLOAD(SE, 0); asm volatile("s_waitcnt vmcnt(0)" ::: "memory"); SWRITE(0, SE); __syncthreads();
;   qkt<DK, QL>(pA0, pA1, K_lds, qr, ql, r32, hi); HOOK(pA0, pA1, 0); partialSM(pA0, pA1, m_reg, mnA, alA, C, thrRaw);
;   SLOAD(SO, KVBLK); if (SD == 2) { if (2 < NT) SLOAD(SE, 2 * KVBLK); }
;   SWAIT(); SWRITE(1, SO); __syncthreads();
.LBB0_680:
	s_andn2_b64 vcc, exec, s[0:1]
	s_cbranch_vccnz .LBB0_369
	v_mov_b32_e32 v73, v188
	v_readlane_b32 s0, v253, 17
	v_readlane_b32 s1, v253, 18
	v_ashrrev_i32_e32 v74, 4, v73
	v_lshlrev_b32_e32 v16, 3, v73
	v_add_u32_e32 v18, 32, v74
	v_ashrrev_i32_e32 v75, 3, v73
	v_mov_b64_e32 v[50:51], s[0:1]
	s_movk_i32 s3, 0x2800
	v_and_b32_e32 v0, 0x78, v16
	v_mad_i64_i32 v[2:3], s[0:1], v74, s3, v[50:51]
	v_mad_i64_i32 v[4:5], s[0:1], v18, s3, v[50:51]
	v_mad_i64_i32 v[10:11], s[0:1], v75, s3, v[50:51]
	v_lshlrev_b32_e32 v52, 1, v0
	v_mov_b32_e32 v53, v1
	v_ashrrev_i32_e32 v0, 1, v73
	s_movk_i32 s0, 0xffe0
	v_lshlrev_b32_e32 v17, 4, v73
	v_lshl_add_u64 v[2:3], v[2:3], 0, v[52:53]
	v_lshl_add_u64 v[6:7], v[4:5], 0, v[52:53]
	v_bfi_b32 v0, s0, v0, v73
	v_readlane_b32 s0, v253, 9
	global_load_dwordx4 v[2:5], v[2:3], off offset:2048
	s_nop 0
	global_load_dwordx4 v[6:9], v[6:7], off offset:2048
	v_and_b32_e32 v54, 0x70, v17
	v_mov_b32_e32 v55, v1
	v_readlane_b32 s1, v253, 10
	v_lshl_add_u64 v[10:11], v[10:11], 0, v[54:55]
	global_load_dwordx4 v[10:13], v[10:11], off offset:1024
	v_mov_b64_e32 v[14:15], s[0:1]
	v_mad_i64_i32 v[14:15], s[0:1], v0, s3, v[14:15]
	v_lshrrev_b32_e32 v0, 1, v73
	v_and_b32_e32 v0, 16, v0
	v_lshl_add_u64 v[14:15], v[14:15], 0, v[0:1]
	global_load_dwordx4 v[110:113], v[14:15], off
	global_load_dwordx4 v[106:109], v[14:15], off offset:32
	global_load_dwordx4 v[98:101], v[14:15], off offset:64
	global_load_dwordx4 v[102:105], v[14:15], off offset:96
	v_add_u32_e32 v84, 64, v74
	v_add_u32_e32 v88, 0x60, v74
	v_add_u32_e32 v92, 64, v75
	v_mad_i64_i32 v[84:85], s[0:1], v84, s3, v[50:51]
	v_mad_i64_i32 v[88:89], s[0:1], v88, s3, v[50:51]
	v_mad_i64_i32 v[92:93], s[0:1], v92, s3, v[50:51]
	v_lshl_add_u64 v[84:85], v[84:85], 0, v[52:53]
	v_lshl_add_u64 v[88:89], v[88:89], 0, v[52:53]
	v_lshl_add_u64 v[92:93], v[92:93], 0, v[54:55]
	global_load_dwordx4 v[84:87], v[84:85], off offset:2048
	global_load_dwordx4 v[88:91], v[88:89], off offset:2048
	global_load_dwordx4 v[92:95], v[92:93], off offset:1024
	v_and_b32_e32 v20, 0xfffff0, v74
	v_lshlrev_b32_e32 v21, 1, v74
	v_lshrrev_b32_e32 v22, 1, v74
	v_and_b32_e32 v24, 3, v74
	v_and_or_b32 v20, v21, 8, v20
	v_and_or_b32 v21, v22, 4, v24
	v_and_b32_e32 v22, 0xfffff0, v18
	v_lshlrev_b32_e32 v18, 1, v18
	v_bfe_u32 v23, v16, 5, 2
	v_lshrrev_b32_e32 v14, 1, v20
	v_and_or_b32 v18, v18, 8, v22
	v_and_b32_e32 v76, 31, v73
	v_or_b32_e32 v14, v14, v23
	v_lshrrev_b32_e32 v18, 1, v18
	v_and_b32_e32 v25, 48, v17
	v_lshlrev_b32_e32 v60, 7, v76
	v_and_b32_e32 v16, 0x70, v16
	v_lshlrev_b32_e32 v15, 6, v21
	v_lshlrev_b32_e32 v14, 9, v14
	v_or_b32_e32 v18, v18, v23
	v_and_b32_e32 v19, 0x70, v73
	v_lshlrev_b32_e32 v26, 7, v75
	v_bitop3_b32 v24, v0, v60, v16 bitop3:0xde
	v_or3_b32 v14, v14, v15, v25
	v_lshlrev_b32_e32 v18, 9, v18
	v_bitop3_b32 v19, v54, v26, v19 bitop3:0xde
	v_add_u32_e32 v212, 0, v24
	v_or3_b32 v15, v18, v15, v25
	v_add_u32_e32 v214, 0, v14
	v_add_u32_e32 v213, 0, v19
	s_waitcnt vmcnt(0)
	v_add_u32_e32 v215, 0, v15
	s_add_i32 s8, 0, 0x10000
	v_and_b32_e32 v77, 63, v73
	v_add_u32_e32 v68, 64, v75
	v_mad_i64_i32 v[58:59], s[0:1], v74, s3, 0
	v_mad_i64_i32 v[56:57], s[0:1], v75, s3, 0
	v_mad_i64_i32 v[68:69], s[0:1], v68, s3, v[50:51]
	s_cmp_lg_u32 0, -1
	s_cselect_b32 s2, 0, 0
	v_lshl_add_u64 v[68:69], v[68:69], 0, v[54:55]
	s_waitcnt vmcnt(6)
	ds_write_b128 v214, v[2:5]
	s_waitcnt vmcnt(5)
	ds_write_b128 v215, v[6:9]
	s_waitcnt vmcnt(4)
	ds_write_b128 v213, v[10:13] offset:32768
	s_waitcnt lgkmcnt(0)
	s_barrier
	ds_read_b128 v[2:5], v212 offset:32768
	ds_read_b128 v[6:9], v212 offset:36864
	s_waitcnt vmcnt(3) lgkmcnt(1)
	v_mfma_f32_32x32x16_bf16 v[18:33], v[2:5], v[110:113], 0
	v_or_b32_e32 v2, 32, v0
	v_bitop3_b32 v2, v2, v60, v16 bitop3:0xde
	v_add_u32_e32 v216, 0, v2
	ds_read_b128 v[2:5], v216 offset:32768
	v_lshlrev_b32_e32 v10, 1, v73
	v_lshlrev_b32_e32 v11, 3, v77
	v_and_b32_e32 v12, 0xc0, v17
	s_waitcnt lgkmcnt(1)
	v_mfma_f32_32x32x16_bf16 v[34:49], v[6:9], v[110:113], 0
	v_and_b32_e32 v6, 0x3fffffc0, v73
	v_lshl_add_u32 v207, v6, 2, s8
	ds_read_b128 v[6:9], v216 offset:36864
	v_and_b32_e32 v10, 32, v10
	v_readlane_b32 s16, v254, 62
	v_readlane_b32 s17, v254, 63
	v_readlane_b32 s18, v255, 0
	s_waitcnt vmcnt(2) lgkmcnt(1)
	v_mfma_f32_32x32x16_bf16 v[18:33], v[2:5], v[106:109], v[18:33]
	v_or_b32_e32 v2, 64, v0
	v_bitop3_b32 v2, v2, v60, v16 bitop3:0xde
	v_add_u32_e32 v217, 0, v2
	ds_read_b128 v[2:5], v217 offset:32768
	v_readlane_b32 s19, v255, 1
	v_readlane_b32 s20, v255, 2
	v_readlane_b32 s21, v255, 3
	s_waitcnt lgkmcnt(1)
	v_mfma_f32_32x32x16_bf16 v[34:49], v[6:9], v[106:109], v[34:49]
	v_and_or_b32 v6, v11, 24, v12
	v_and_b32_e32 v7, 0x100, v11
	v_or3_b32 v78, v6, v10, v7
	ds_read_b128 v[6:9], v217 offset:36864
	v_readlane_b32 s22, v255, 4
	v_readlane_b32 s23, v255, 5
	v_readlane_b32 s24, v255, 6
	s_waitcnt vmcnt(1) lgkmcnt(1)
	v_mfma_f32_32x32x16_bf16 v[18:33], v[2:5], v[98:101], v[18:33]
	v_or_b32_e32 v2, 0x60, v0
	v_bitop3_b32 v2, v2, v60, v16 bitop3:0xde
	v_add_u32_e32 v218, 0, v2
	ds_read_b128 v[2:5], v218 offset:32768
	ds_read_b128 v[60:63], v218 offset:36864
	v_readlane_b32 s25, v255, 7
	v_readlane_b32 s26, v255, 8
	s_waitcnt lgkmcnt(2)
	v_mfma_f32_32x32x16_bf16 v[34:49], v[6:9], v[98:101], v[34:49]
	v_readlane_b32 s27, v255, 9
	v_readlane_b32 s28, v255, 10
	v_readlane_b32 s29, v255, 11
	v_readlane_b32 s30, v255, 12
	v_readlane_b32 s31, v255, 13
	s_mov_b32 s16, s17
	v_add_u32_e32 v211, s2, v78
	s_waitcnt vmcnt(0) lgkmcnt(1)
	v_mfma_f32_32x32x16_bf16 v[18:33], v[2:5], v[102:105], v[18:33]
	s_mov_b32 s18, s17
	s_mov_b32 s19, s17
	s_mov_b32 s20, s17
	s_mov_b32 s21, s17
	s_mov_b32 s22, s17
	s_mov_b32 s23, s17
	s_mov_b32 s24, s17
	s_waitcnt lgkmcnt(0)
; #define SLOAD(i, k0) do { sr_[i].vs0 = *reinterpret_cast<const bf16x8*>(&Vh[(long)((k0) + sr) * LDP + sc]); sr_[i].vs1 = *reinterpret_cast<const bf16x8*>(&Vh[(long)((k0) + 32 + sr) * LDP + sc]); \
;     sr_[i].ks0 = *reinterpret_cast<const bf16x8*>(&Kh[(long)((k0) + ksr) * LDP + ksc]); if (DK == 128) sr_[i].ks1 = *reinterpret_cast<const bf16x8*>(&Kh[(long)((k0) + 32 + ksr) * LDP + ksc]); } while (0)
; #define SWAIT() do { if (SD == 1) asm volatile("s_waitcnt vmcnt(0)" ::: "memory"); else if (DK == 128) asm volatile("s_waitcnt vmcnt(4)" ::: "memory"); else asm volatile("s_waitcnt vmcnt(3)" ::: "memory"); } while (0)
; #define HOOK(P0, P1, j) do { if (NA) na_hook(P0, P1, krow0 + (j), q_row, q_col, win_r, win_c, rpb, inv_scale, hi); } while (0)
; __device__ __forceinline__ void partialSM(f32x16& p0, f32x16& p1, float& m_reg, float& mn, float& alpha, float C, float thrRaw) {
;   float pmax = p0[0];
; #pragma unroll
;   for (int r = 1; r < 16; ++r) pmax = fmaxf(pmax, p0[r]);
; #pragma unroll
;   for (int r = 0; r < 16; ++r) pmax = fmaxf(pmax, p1[r]);
;   { auto rr = __builtin_amdgcn_permlane32_swap(__float_as_uint(pmax), __float_as_uint(pmax), false, false);
;     pmax = fmaxf(__uint_as_float(rr[0]), __uint_as_float(rr[1])); }
;   if (__builtin_expect(__all(pmax - m_reg <= thrRaw), 1)) { mn = m_reg; alpha = 1.f; }
;   else { mn = fmaxf(m_reg, pmax); alpha = __builtin_amdgcn_exp2f((m_reg - mn) * C); m_reg = mn; }
;   float mnC = -mn * C;
; #pragma unroll
;   for (int r = 0; r < 16; ++r) p0[r] = fmaf(p0[r], C, mnC);
; #pragma unroll
;   for (int r = 0; r < 16; ++r) p1[r] = fmaf(p1[r], C, mnC);
; #pragma unroll
;   for (int r = 0; r < 16; ++r) p0[r] = __builtin_amdgcn_exp2f(p0[r]);
; template <int DK, bool NA, bool QL, int SD> ...
;     ...
;   SLOAD(SE, 0); asm volatile("s_waitcnt vmcnt(0)" ::: "memory"); SWRITE(0, SE); __syncthreads();
;   qkt<DK, QL>(pA0, pA1, K_lds, qr, ql, r32, hi); HOOK(pA0, pA1, 0); partialSM(pA0, pA1, m_reg, mnA, alA, C, thrRaw);
;   SLOAD(SO, KVBLK); if (SD == 2) { if (2 < NT) SLOAD(SE, 2 * KVBLK); }
;   SWAIT(); SWRITE(1, SO); __syncthreads();
	v_mfma_f32_32x32x16_bf16 v[34:49], v[60:63], v[102:105], v[34:49]
	s_nop 2
	v_max_f32_e32 v60, v19, v19
	v_max_f32_e32 v61, v18, v18
	v_max_f32_e32 v60, v61, v60
	v_max3_f32 v60, v60, v20, v21
	v_max3_f32 v60, v60, v22, v23
	v_max3_f32 v60, v60, v24, v25
	v_max3_f32 v60, v60, v26, v27
	v_max3_f32 v60, v60, v28, v29
	v_max3_f32 v60, v60, v30, v31
	v_max3_f32 v60, v60, v32, v33
	v_max3_f32 v60, v60, v34, v35
	v_max3_f32 v60, v60, v36, v37
	v_max3_f32 v60, v60, v38, v39
	v_max3_f32 v60, v60, v40, v41
	v_max3_f32 v72, v60, v42, v43
	v_max3_f32 v72, v72, v44, v45
	v_max3_f32 v72, v72, v46, v47
	v_max3_f32 v72, v72, v48, v49
	v_mov_b32_e32 v79, v72
	s_nop 1
	v_permlane32_swap_b32_e32 v72, v79
	v_add_u32_e32 v60, 64, v74
	v_add_u32_e32 v62, 0x60, v74
	v_max_f32_e32 v79, v79, v79
	v_max_f32_e32 v72, v72, v72
	v_mad_i64_i32 v[60:61], s[0:1], v60, s3, v[50:51]
	v_mad_i64_i32 v[62:63], s[0:1], v62, s3, v[50:51]
	v_max_f32_e32 v72, v72, v79
	v_add_f32_e32 v79, 0x7149f2ca, v72
	s_mov_b32 s0, 0x42800000
	v_max_f32_e32 v72, 0xf149f2ca, v72
	v_cmp_ge_f32_e32 vcc, s0, v79
	v_sub_f32_e32 v79, 0xf149f2ca, v72
	v_mul_f32_e32 v79, 0x3e38aa3b, v79
	v_exp_f32_e32 v79, v79
	s_cmp_eq_u64 vcc, exec
	s_cselect_b64 vcc, -1, 0
	v_cndmask_b32_e32 v142, v72, v199, vcc
	v_mul_f32_e32 v72, 0xbe38aa3b, v142
	v_cndmask_b32_e64 v219, v79, 1.0, vcc
	v_fmamk_f32 v79, v18, 0x3e38aa3b, v72
	v_add_u32_e32 v18, 0x80, v75
	v_fmamk_f32 v80, v19, 0x3e38aa3b, v72
	v_mad_i64_i32 v[18:19], s[0:1], v18, s3, v[50:51]
	v_lshl_add_u64 v[60:61], v[60:61], 0, v[52:53]
	v_lshl_add_u64 v[64:65], v[62:63], 0, v[52:53]
	v_lshl_add_u64 v[18:19], v[18:19], 0, v[54:55]
	s_nop 0
	v_fmamk_f32 v81, v20, 0x3e38aa3b, v72
	v_add_u32_e32 v20, 0x80, v74
	global_load_dwordx4 v[122:125], v[18:19], off offset:1024
	v_add_u32_e32 v18, 0xa0, v74
	v_mad_i64_i32 v[18:19], s[0:1], v18, s3, v[50:51]
	v_fmamk_f32 v82, v21, 0x3e38aa3b, v72
	v_lshl_add_u64 v[18:19], v[18:19], 0, v[52:53]
	v_mad_i64_i32 v[20:21], s[0:1], v20, s3, v[50:51]
	v_lshl_add_u64 v[20:21], v[20:21], 0, v[52:53]
	global_load_dwordx4 v[118:121], v[18:19], off offset:2048
	global_load_dwordx4 v[114:117], v[20:21], off offset:2048
	v_mov_b32_e32 v20, v72
	v_fmamk_f32 v22, v22, 0x3e38aa3b, v72
	v_fmamk_f32 v23, v23, 0x3e38aa3b, v72
	v_fmamk_f32 v24, v24, 0x3e38aa3b, v72
	v_fmamk_f32 v25, v25, 0x3e38aa3b, v72
	v_fmamk_f32 v26, v26, 0x3e38aa3b, v72
	v_fmamk_f32 v27, v27, 0x3e38aa3b, v72
	v_fmamk_f32 v28, v28, 0x3e38aa3b, v72
	v_fmamk_f32 v29, v29, 0x3e38aa3b, v72
	v_fmamk_f32 v30, v30, 0x3e38aa3b, v72
	v_fmamk_f32 v18, v31, 0x3e38aa3b, v72
	v_fmamk_f32 v19, v32, 0x3e38aa3b, v72
	v_fmac_f32_e32 v20, 0x3e38aa3b, v33
	s_mov_b32 s25, s17
	s_mov_b32 s26, s17
	s_mov_b32 s27, s17
	s_mov_b32 s28, s17
	s_mov_b32 s29, s17
	s_mov_b32 s30, s17
	s_mov_b32 s31, s17
	v_mov_b64_e32 v[2:3], s[16:17]
	v_exp_f32_e32 v177, v79
	v_exp_f32_e32 v226, v80
	v_exp_f32_e32 v161, v81
	v_exp_f32_e32 v223, v82
	v_exp_f32_e32 v153, v22
	v_exp_f32_e32 v176, v23
	v_exp_f32_e32 v152, v24
	v_exp_f32_e32 v160, v25
	v_exp_f32_e32 v149, v26
	v_exp_f32_e32 v151, v27
	v_exp_f32_e32 v147, v28
	v_exp_f32_e32 v150, v29
	v_exp_f32_e32 v145, v30
	v_exp_f32_e32 v148, v18
	v_exp_f32_e32 v144, v19
	v_exp_f32_e32 v146, v20
	s_addk_i32 s2, 0x4000
	v_and_b32_e32 v18, 15, v73
	v_mov_b64_e32 v[16:17], s[30:31]
	s_waitcnt vmcnt(3)
	v_add_u32_e32 v210, s2, v78
	v_lshl_or_b32 v58, v18, 4, v58
	v_readlane_b32 s2, v254, 34
	v_and_b32_e32 v18, 7, v73
	v_mov_b64_e32 v[4:5], s[18:19]
	v_mov_b64_e32 v[6:7], s[20:21]
	v_mov_b64_e32 v[8:9], s[22:23]
	v_mov_b64_e32 v[10:11], s[24:25]
	v_mov_b64_e32 v[12:13], s[26:27]
	v_mov_b64_e32 v[14:15], s[28:29]
	s_mov_b32 s0, 0x3e38aa3b
	v_readlane_b32 s3, v254, 35
	v_lshl_or_b32 v56, v18, 4, v56
	v_mov_b32_e32 v209, 0
	v_mov_b64_e32 v[32:33], v[16:17]
	s_mov_b32 s9, 1
	s_mov_b32 s13, s17
	v_pk_fma_f32 v[132:133], v[48:49], s[0:1], v[72:73] op_sel_hi:[1,0,0]
	v_pk_fma_f32 v[134:135], v[46:47], s[0:1], v[72:73] op_sel_hi:[1,0,0]
	v_pk_fma_f32 v[140:141], v[44:45], s[0:1], v[72:73] op_sel_hi:[1,0,0]
	v_pk_fma_f32 v[126:127], v[42:43], s[0:1], v[72:73] op_sel_hi:[1,0,0]
	v_pk_fma_f32 v[128:129], v[40:41], s[0:1], v[72:73] op_sel_hi:[1,0,0]
	v_pk_fma_f32 v[130:131], v[38:39], s[0:1], v[72:73] op_sel_hi:[1,0,0]
	v_pk_fma_f32 v[136:137], v[36:37], s[0:1], v[72:73] op_sel_hi:[1,0,0]
	v_pk_fma_f32 v[138:139], v[34:35], s[0:1], v[72:73] op_sel_hi:[1,0,0]
	s_waitcnt vmcnt(5)
	ds_write_b128 v214, v[84:87] offset:16384
	s_waitcnt vmcnt(4)
	ds_write_b128 v215, v[88:91] offset:16384
	s_waitcnt vmcnt(3)
	ds_write_b128 v213, v[92:95] offset:49152
	v_cmp_gt_u32_e64 s[0:1], 32, v77
	v_lshl_add_u32 v208, v76, 2, v207
	v_lshl_add_u64 v[156:157], s[2:3], 0, v[58:59]
	v_lshl_add_u64 v[158:159], s[2:3], 0, v[56:57]
	v_mov_b64_e32 v[30:31], v[14:15]
	v_mov_b64_e32 v[28:29], v[12:13]
	v_mov_b64_e32 v[26:27], v[10:11]
	v_mov_b64_e32 v[24:25], v[8:9]
	v_mov_b64_e32 v[22:23], v[6:7]
	v_mov_b64_e32 v[20:21], v[4:5]
	v_mov_b64_e32 v[18:19], v[2:3]
	v_mov_b32_e32 v34, 0
	v_mov_b32_e32 v35, v209
	v_mov_b32_e32 v36, v209
	v_mov_b32_e32 v37, v209
	v_mov_b32_e32 v38, v209
	v_mov_b32_e32 v39, v209
	v_mov_b32_e32 v40, v209
	v_mov_b32_e32 v41, v209
	v_mov_b32_e32 v42, v209
	v_mov_b32_e32 v43, v209
	v_mov_b32_e32 v44, v209
	v_mov_b32_e32 v45, v209
	v_mov_b32_e32 v46, v209
	v_mov_b32_e32 v47, v209
	v_mov_b32_e32 v48, v209
	v_mov_b32_e32 v49, v209
	v_mov_b32_e32 v50, 0
	v_mov_b32_e32 v51, v209
	v_mov_b32_e32 v52, v209
	v_mov_b32_e32 v53, v209
	v_mov_b32_e32 v54, v209
	v_mov_b32_e32 v55, v209
	v_mov_b32_e32 v56, v209
	v_mov_b32_e32 v57, v209
	v_mov_b32_e32 v58, v209
	v_mov_b32_e32 v59, v209
	v_mov_b32_e32 v60, v209
	v_mov_b32_e32 v61, v209
	v_mov_b32_e32 v62, v209
	v_mov_b32_e32 v63, v209
	v_mov_b32_e32 v64, v209
	v_mov_b32_e32 v65, v209
	s_waitcnt lgkmcnt(0)
	s_barrier

; #define SBAR() __builtin_amdgcn_sched_barrier(0)
; #define RESC(a) do { if (__any((a) < 1.f)) { if (hi == 0) al_l[r32] = (a); asm volatile("s_waitcnt lgkmcnt(0)" ::: "memory"); \
;     _Pragma("unroll") for (int d = 0; d < 4; ++d) _Pragma("unroll") for (int r = 0; r < 16; ++r) o[d][r] *= al_l[crow(r, hi)]; } } while (0)
; #define HOOK(P0, P1, j) do { if (NA) na_hook(P0, P1, krow0 + (j), q_row, q_col, win_r, win_c, rpb, inv_scale, hi); } while (0)
; __device__ __forceinline__ void finishSM(f32x16& p0, f32x16& p1, float alpha, float& l_reg, bf16x8& pa0, bf16x8& pa1, bf16x8& pa2, bf16x8& pa3) {
; #pragma unroll
;   for (int r = 0; r < 16; ++r) p1[r] = __builtin_amdgcn_exp2f(p1[r]);
;   float ps = 0;
; #pragma unroll
;   for (int r = 0; r < 16; ++r) ps += p0[r];
; #pragma unroll
;   for (int r = 0; r < 16; ++r) ps += p1[r];
;   { auto rr = __builtin_amdgcn_permlane32_swap(__float_as_uint(ps), __float_as_uint(ps), false, false);
;     ps = __uint_as_float(rr[0]) + __uint_as_float(rr[1]); }
;   l_reg = l_reg * alpha + ps;
;     ...
;   PK4(p0, 0, pa0); PK4(p0, 8, pa1); PK4(p1, 0, pa2); PK4(p1, 8, pa3);
;     ...
; }
; template <int DK, bool NA, bool QL, int SD> ...
;     ...
;   SBAR(); qkt<DK, QL>(pB0, pB1, (bf16*)((char*)K_lds + SHM_K), qr, ql, r32, hi); HOOK(pB0, pB1, NT - 1);
;   finishSM(pA0, pA1, alA, l_reg, pa0, pa1, pa2, pa3); SBAR();
;   pv_d0(o, vb0, pa0, pa1, pa2, pa3); partialSM(pB0, pB1, m_reg, mnB, alB, C, thrRaw);
;   __syncthreads(); RESC(alB);
;   finishSM(pB0, pB1, alB, l_reg, pa0, pa1, pa2, pa3); SBAR();
;   pv_d0(o, vb0 + (int)SHM_V, pa0, pa1, pa2, pa3);
.LBB0_698:
	v_cndmask_b32_e64 v101, v101, v142, s[2:3]
	v_mul_f32_e32 v101, 0xbe38aa3b, v101
	v_fmamk_f32 v82, v82, 0x3e38aa3b, v101
	v_fmamk_f32 v83, v83, 0x3e38aa3b, v101
	v_fmamk_f32 v102, v84, 0x3e38aa3b, v101
	v_exp_f32_e32 v84, v82
	v_fmamk_f32 v103, v86, 0x3e38aa3b, v101
	v_exp_f32_e32 v86, v83
	v_fmamk_f32 v85, v85, 0x3e38aa3b, v101
	v_exp_f32_e32 v82, v102
	v_fmamk_f32 v66, v66, 0x3e38aa3b, v101
	v_exp_f32_e32 v85, v85
	v_fmamk_f32 v104, v87, 0x3e38aa3b, v101
	v_fmamk_f32 v113, v96, 0x3e38aa3b, v101
	v_fmamk_f32 v96, v77, 0x3e38aa3b, v101
	v_exp_f32_e32 v77, v103
	v_exp_f32_e32 v102, v66
	v_add_f32_e32 v66, 0, v84
	v_fmamk_f32 v105, v88, 0x3e38aa3b, v101
	v_exp_f32_e32 v83, v104
	v_add_f32_e32 v66, v86, v66
	v_fmamk_f32 v106, v89, 0x3e38aa3b, v101
	v_fmamk_f32 v112, v95, 0x3e38aa3b, v101
	v_fmamk_f32 v95, v76, 0x3e38aa3b, v101
	v_exp_f32_e32 v76, v105
	v_add_f32_e32 v66, v82, v66
	v_fmamk_f32 v107, v90, 0x3e38aa3b, v101
	v_fmamk_f32 v114, v97, 0x3e38aa3b, v101
	v_fmamk_f32 v97, v78, 0x3e38aa3b, v101
	v_exp_f32_e32 v78, v106
	v_add_f32_e32 v66, v85, v66
	v_fmamk_f32 v108, v91, 0x3e38aa3b, v101
	v_fmamk_f32 v109, v92, 0x3e38aa3b, v101
	v_fmamk_f32 v92, v73, 0x3e38aa3b, v101
	v_exp_f32_e32 v73, v107
	v_add_f32_e32 v66, v77, v66
	v_fmamk_f32 v111, v94, 0x3e38aa3b, v101
	v_fmamk_f32 v94, v75, 0x3e38aa3b, v101
	v_exp_f32_e32 v75, v108
	v_add_f32_e32 v66, v83, v66
	v_fmamk_f32 v110, v93, 0x3e38aa3b, v101
	v_fmamk_f32 v90, v71, 0x3e38aa3b, v101
	v_exp_f32_e32 v71, v109
	v_add_f32_e32 v66, v76, v66
	v_fmamk_f32 v93, v74, 0x3e38aa3b, v101
	v_exp_f32_e32 v74, v110
	v_add_f32_e32 v66, v78, v66
	v_fmamk_f32 v88, v69, 0x3e38aa3b, v101
	v_exp_f32_e32 v69, v111
	v_add_f32_e32 v66, v73, v66
	v_fmamk_f32 v91, v72, 0x3e38aa3b, v101
	v_exp_f32_e32 v72, v112
	v_add_f32_e32 v66, v75, v66
	v_fmamk_f32 v87, v68, 0x3e38aa3b, v101
	v_exp_f32_e32 v68, v113
	v_add_f32_e32 v66, v71, v66
	v_fmamk_f32 v89, v70, 0x3e38aa3b, v101
	v_exp_f32_e32 v70, v114
	v_add_f32_e32 v66, v74, v66
	v_fmamk_f32 v67, v67, 0x3e38aa3b, v101
	v_add_f32_e32 v66, v69, v66
	v_exp_f32_e32 v103, v67
	v_add_f32_e32 v66, v72, v66
	v_exp_f32_e32 v87, v87
	v_add_f32_e32 v66, v68, v66
	v_exp_f32_e32 v88, v88
	v_add_f32_e32 v66, v70, v66
	v_exp_f32_e32 v89, v89
	v_add_f32_e32 v66, v102, v66
	v_exp_f32_e32 v90, v90
	v_add_f32_e32 v66, v103, v66
	v_exp_f32_e32 v91, v91
	v_add_f32_e32 v66, v87, v66
	v_exp_f32_e32 v92, v92
	v_add_f32_e32 v66, v88, v66
	v_exp_f32_e32 v93, v93
	v_add_f32_e32 v66, v89, v66
	v_exp_f32_e32 v94, v94
	v_add_f32_e32 v66, v90, v66
	v_exp_f32_e32 v95, v95
	v_add_f32_e32 v66, v91, v66
	v_exp_f32_e32 v96, v96
	v_add_f32_e32 v66, v92, v66
	v_fmamk_f32 v79, v79, 0x3e38aa3b, v101
	v_exp_f32_e32 v97, v97
	v_add_f32_e32 v66, v93, v66
	v_fmamk_f32 v80, v80, 0x3e38aa3b, v101
	v_exp_f32_e32 v104, v79
	v_add_f32_e32 v66, v94, v66
	v_fmac_f32_e32 v101, 0x3e38aa3b, v81
	v_exp_f32_e32 v105, v80
	v_add_f32_e32 v66, v95, v66
	v_exp_f32_e32 v101, v101
	v_add_f32_e32 v66, v96, v66
	v_add_f32_e32 v66, v97, v66
	v_add_f32_e32 v66, v104, v66
	v_add_f32_e32 v66, v105, v66
	v_add_f32_e32 v66, v101, v66
	v_mov_b32_e32 v67, v66
	s_nop 1
	v_permlane32_swap_b32_e32 v66, v67
	v_cvt_pk_bf16_f32 v80, v84, v86
	v_cvt_pk_bf16_f32 v81, v82, v85
	v_cvt_pk_bf16_f32 v82, v77, v83
	v_cvt_pk_bf16_f32 v83, v76, v78
	v_cvt_pk_bf16_f32 v76, v73, v75
	v_cvt_pk_bf16_f32 v77, v71, v74
	v_cvt_pk_bf16_f32 v78, v69, v72
	v_cvt_pk_bf16_f32 v79, v68, v70
	v_cvt_pk_bf16_f32 v68, v102, v103
	v_cvt_pk_bf16_f32 v69, v87, v88
	v_cvt_pk_bf16_f32 v70, v89, v90
	v_cvt_pk_bf16_f32 v71, v91, v92
	v_cvt_pk_bf16_f32 v72, v93, v94
	v_cvt_pk_bf16_f32 v73, v95, v96
	v_cvt_pk_bf16_f32 v74, v97, v104
	v_cvt_pk_bf16_f32 v75, v105, v101
	s_nop 0
	v_permlane32_swap_b32_e32 v80, v82
	v_permlane32_swap_b32_e32 v81, v83
	v_permlane32_swap_b32_e32 v76, v78
	v_permlane32_swap_b32_e32 v77, v79
	v_permlane32_swap_b32_e32 v68, v70
	v_permlane32_swap_b32_e32 v69, v71
	v_permlane32_swap_b32_e32 v72, v74
	v_permlane32_swap_b32_e32 v73, v75
	ds_read_b64_tr_b16 v[84:85], v210 offset:0
	ds_read_b64_tr_b16 v[86:87], v210 offset:0x800
	ds_read_b64_tr_b16 v[88:89], v210 offset:0x1000
	ds_read_b64_tr_b16 v[90:91], v210 offset:0x1800
	ds_read_b64_tr_b16 v[92:93], v210 offset:0x2000
	ds_read_b64_tr_b16 v[94:95], v210 offset:0x2800
	ds_read_b64_tr_b16 v[102:103], v210 offset:0x3000
	ds_read_b64_tr_b16 v[104:105], v210 offset:0x3800
	s_waitcnt lgkmcnt(0)
	s_nop 0
	v_mfma_f32_32x32x16_bf16 v[18:33], v[80:83], v[84:87], v[18:33]
	ds_read_b64_tr_b16 v[84:85], v210 offset:0x200
	ds_read_b64_tr_b16 v[86:87], v210 offset:0xa00
	v_mfma_f32_32x32x16_bf16 v[18:33], v[76:79], v[88:91], v[18:33]
	ds_read_b64_tr_b16 v[88:89], v210 offset:0x1200
	ds_read_b64_tr_b16 v[90:91], v210 offset:0x1a00
	v_mfma_f32_32x32x16_bf16 v[18:33], v[68:71], v[92:95], v[18:33]
	ds_read_b64_tr_b16 v[92:93], v210 offset:0x2200
	ds_read_b64_tr_b16 v[94:95], v210 offset:0x2a00
	v_mfma_f32_32x32x16_bf16 v[18:33], v[72:75], v[102:105], v[18:33]
	ds_read_b64_tr_b16 v[102:103], v210 offset:0x3200
	ds_read_b64_tr_b16 v[104:105], v210 offset:0x3a00
	s_waitcnt lgkmcnt(0)
	v_mfma_f32_32x32x16_bf16 v[2:17], v[80:83], v[84:87], v[2:17]
	ds_read_b64_tr_b16 v[84:85], v210 offset:0x400
	ds_read_b64_tr_b16 v[86:87], v210 offset:0xc00
	v_mfma_f32_32x32x16_bf16 v[2:17], v[76:79], v[88:91], v[2:17]
	ds_read_b64_tr_b16 v[88:89], v210 offset:0x1400
	ds_read_b64_tr_b16 v[90:91], v210 offset:0x1c00
	v_mfma_f32_32x32x16_bf16 v[2:17], v[68:71], v[92:95], v[2:17]
	ds_read_b64_tr_b16 v[92:93], v210 offset:0x2400
	ds_read_b64_tr_b16 v[94:95], v210 offset:0x2c00
	v_mfma_f32_32x32x16_bf16 v[2:17], v[72:75], v[102:105], v[2:17]
	ds_read_b64_tr_b16 v[102:103], v210 offset:0x3400
	ds_read_b64_tr_b16 v[104:105], v210 offset:0x3c00
	s_waitcnt lgkmcnt(0)
; __device__ __forceinline__ int opaque_tid() { int t = threadIdx.x; asm volatile("" : "+v"(t)); return t; }
; __device__ __forceinline__ int crow(int r, int hi) { return (r & 3) + 8 * (r >> 2) + 4 * hi; }
; __device__ __forceinline__ unsigned cvtpk(float lo, float hi) { unsigned r; asm volatile("v_cvt_pk_bf16_f32 %0, %1, %2" : "=v"(r) : "v"(lo), "v"(hi)); return r; }
; template <int DK, bool NA, bool QL, int SD> ...
;     ...
;   if (hi == 0) li_l[r32] = l_reg; asm volatile("s_waitcnt vmcnt(0) lgkmcnt(0)" ::: "memory");
; #pragma unroll
;   for (int r = 0; r < 16; ++r) { const float rl = __builtin_amdgcn_rcpf(li_l[crow(r, hi)]);
; #pragma unroll
;     for (int d = 0; d < 4; ++d) o[d][r] *= rl; }
; __global__ void __launch_bounds__(NTHR) mega_fwd(Params p) {
;     ...
;                     { const int t2 = opaque_tid(); v4u* STv = (v4u*)((char*)lds + 69632) + t2;
; #pragma unroll
;                       for (int k = 0; k < 8; ++k) { const int d = k >> 1, r0 = 8 * (k & 1); v4u w;
;                           w.x = att::cvtpk(o[d][r0], o[d][r0 + 1]); w.y = att::cvtpk(o[d][r0 + 2], o[d][r0 + 3]); w.z = att::cvtpk(o[d][r0 + 4], o[d][r0 + 5]); w.w = att::cvtpk(o[d][r0 + 6], o[d][r0 + 7]);
;                           STv[k * 512] = w; } }
	v_mfma_f32_32x32x16_bf16 v[50:65], v[80:83], v[84:87], v[50:65]
	ds_read_b64_tr_b16 v[84:85], v210 offset:0x600
	ds_read_b64_tr_b16 v[86:87], v210 offset:0xe00
	v_mfma_f32_32x32x16_bf16 v[50:65], v[76:79], v[88:91], v[50:65]
	ds_read_b64_tr_b16 v[88:89], v210 offset:0x1600
	ds_read_b64_tr_b16 v[90:91], v210 offset:0x1e00
	v_mfma_f32_32x32x16_bf16 v[50:65], v[68:71], v[92:95], v[50:65]
	ds_read_b64_tr_b16 v[92:93], v210 offset:0x2600
	ds_read_b64_tr_b16 v[94:95], v210 offset:0x2e00
	v_mfma_f32_32x32x16_bf16 v[50:65], v[72:75], v[102:105], v[50:65]
	ds_read_b64_tr_b16 v[102:103], v210 offset:0x3600
	ds_read_b64_tr_b16 v[104:105], v210 offset:0x3e00
	s_waitcnt lgkmcnt(0)
	v_mfma_f32_32x32x16_bf16 v[34:49], v[80:83], v[84:87], v[34:49]
	v_mfma_f32_32x32x16_bf16 v[34:49], v[76:79], v[88:91], v[34:49]
	v_mfma_f32_32x32x16_bf16 v[34:49], v[68:71], v[92:95], v[34:49]
	v_mfma_f32_32x32x16_bf16 v[34:49], v[72:75], v[102:105], v[34:49]
	s_and_saveexec_b64 s[2:3], s[0:1]
	v_add_f32_e32 v68, v98, v99
	v_fmac_f32_e32 v68, v209, v143
	v_add_f32_e32 v66, v66, v67
	v_fmac_f32_e32 v66, v68, v100
	ds_write_b32 v208, v66
	s_or_b64 exec, exec, s[2:3]
	s_waitcnt vmcnt(0) lgkmcnt(0)
	v_add_u32_e32 v0, v207, v0
	ds_read_b128 v[66:69], v0
	ds_read_b128 v[70:73], v0 offset:32
	v_readlane_b32 s0, v253, 17
	v_readlane_b32 s1, v253, 18
	s_movk_i32 s3, 0x2800
	s_waitcnt lgkmcnt(1)
	v_rcp_f32_e32 v66, v66
	v_rcp_f32_e32 v67, v67
	s_cmp_lg_u32 0, -1
	s_cselect_b32 s2, 0, 0
	v_mul_f32_e32 v75, v66, v2
	v_rcp_f32_e32 v2, v68
	v_mul_f32_e32 v68, v67, v3
	v_rcp_f32_e32 v3, v69
	v_mul_f32_e32 v74, v66, v18
	v_mul_f32_e32 v50, v66, v50
	v_mul_f32_e32 v34, v66, v34
	v_mul_f32_e32 v66, v67, v19
	v_mul_f32_e32 v51, v67, v51
	v_mul_f32_e32 v35, v67, v35
	v_mul_f32_e32 v67, v2, v20
	v_mul_f32_e32 v69, v2, v4
	v_mul_f32_e32 v52, v2, v52
	v_mul_f32_e32 v36, v2, v36
	v_mul_f32_e32 v76, v3, v21
	s_waitcnt lgkmcnt(0)
	v_rcp_f32_e32 v2, v70
	v_mul_f32_e32 v70, v3, v5
	v_mul_f32_e32 v53, v3, v53
	v_mul_f32_e32 v37, v3, v37
	v_rcp_f32_e32 v3, v71
	v_mul_f32_e32 v22, v2, v22
	v_mul_f32_e32 v6, v2, v6
	v_mul_f32_e32 v54, v2, v54
	v_mul_f32_e32 v38, v2, v38
	v_mul_f32_e32 v23, v3, v23
	v_mul_f32_e32 v7, v3, v7
	v_mul_f32_e32 v55, v3, v55
	v_mul_f32_e32 v39, v3, v39
	ds_read_b128 v[2:5], v0 offset:64
	v_rcp_f32_e32 v18, v72
	v_rcp_f32_e32 v71, v73
	s_mov_b32 s12, s13
	s_mov_b32 s14, s13
	v_mul_f32_e32 v24, v18, v24
	v_mul_f32_e32 v8, v18, v8
	v_mul_f32_e32 v56, v18, v56
	v_mul_f32_e32 v40, v18, v40
	ds_read_b128 v[18:21], v0 offset:96
	s_waitcnt lgkmcnt(1)
	v_rcp_f32_e32 v0, v2
	v_rcp_f32_e32 v2, v3
	v_rcp_f32_e32 v3, v4
	v_mul_f32_e32 v25, v71, v25
	v_mul_f32_e32 v26, v0, v26
	v_mul_f32_e32 v10, v0, v10
	v_mul_f32_e32 v58, v0, v58
	v_mul_f32_e32 v0, v0, v42
	v_mul_f32_e32 v27, v2, v27
	v_mul_f32_e32 v11, v2, v11
	v_mul_f32_e32 v42, v2, v59
	v_mul_f32_e32 v43, v2, v43
	v_rcp_f32_e32 v2, v5
	v_mul_f32_e32 v28, v3, v28
	v_mul_f32_e32 v12, v3, v12
	v_mul_f32_e32 v59, v3, v60
	v_mul_f32_e32 v44, v3, v44
	v_mul_f32_e32 v29, v2, v29
	s_waitcnt lgkmcnt(0)
	v_rcp_f32_e32 v3, v18
	v_mul_f32_e32 v13, v2, v13
	v_mul_f32_e32 v18, v2, v61
	v_mul_f32_e32 v45, v2, v45
	v_rcp_f32_e32 v2, v19
	v_mul_f32_e32 v30, v3, v30
	v_mul_f32_e32 v14, v3, v14
	v_mul_f32_e32 v19, v3, v62
	v_mul_f32_e32 v46, v3, v46
	v_mul_f32_e32 v31, v2, v31
	v_rcp_f32_e32 v3, v20
	v_mul_f32_e32 v15, v2, v15
	v_mul_f32_e32 v20, v2, v63
	v_mul_f32_e32 v47, v2, v47
	v_rcp_f32_e32 v2, v21
	v_mul_f32_e32 v32, v3, v32
	v_mul_f32_e32 v16, v3, v16
	v_mul_f32_e32 v21, v3, v64
	v_mul_f32_e32 v33, v2, v33
	v_mul_f32_e32 v17, v2, v17
	v_mul_f32_e32 v60, v2, v65
	v_mul_f32_e32 v49, v2, v49
	v_mov_b32_e32 v2, v188
	v_mul_f32_e32 v48, v3, v48
	v_lshl_add_u32 v2, v2, 4, 0
	v_add_u32_e32 v61, 0x11000, v2
	v_cvt_pk_bf16_f32 v2, v74, v66
	v_cvt_pk_bf16_f32 v3, v67, v76
	v_cvt_pk_bf16_f32 v4, v22, v23
	v_cvt_pk_bf16_f32 v5, v24, v25
	ds_write_b128 v61, v[2:5]
	v_cvt_pk_bf16_f32 v2, v26, v27
	v_cvt_pk_bf16_f32 v3, v28, v29
	v_cvt_pk_bf16_f32 v4, v30, v31
	v_cvt_pk_bf16_f32 v5, v32, v33
	v_mul_f32_e32 v9, v71, v9
	ds_write_b128 v61, v[2:5] offset:8192
	v_cvt_pk_bf16_f32 v2, v75, v68
	v_cvt_pk_bf16_f32 v3, v69, v70
	v_cvt_pk_bf16_f32 v4, v6, v7
	v_cvt_pk_bf16_f32 v5, v8, v9
	ds_write_b128 v61, v[2:5] offset:16384
	v_cvt_pk_bf16_f32 v2, v10, v11
	v_cvt_pk_bf16_f32 v3, v12, v13
	v_cvt_pk_bf16_f32 v4, v14, v15
	v_cvt_pk_bf16_f32 v5, v16, v17
	v_mul_f32_e32 v57, v71, v57
	ds_write_b128 v61, v[2:5] offset:24576
	v_cvt_pk_bf16_f32 v2, v50, v51
	v_cvt_pk_bf16_f32 v3, v52, v53
	v_cvt_pk_bf16_f32 v4, v54, v55
	v_cvt_pk_bf16_f32 v5, v56, v57
	ds_write_b128 v61, v[2:5] offset:32768
	v_cvt_pk_bf16_f32 v2, v58, v42
	v_cvt_pk_bf16_f32 v3, v59, v18
	v_cvt_pk_bf16_f32 v4, v19, v20
	v_cvt_pk_bf16_f32 v5, v21, v60
	v_mul_f32_e32 v41, v71, v41
	ds_write_b128 v61, v[2:5] offset:40960
	v_cvt_pk_bf16_f32 v2, v34, v35
	v_cvt_pk_bf16_f32 v3, v36, v37
	v_cvt_pk_bf16_f32 v4, v38, v39
	v_cvt_pk_bf16_f32 v5, v40, v41
	v_mov_b32_e32 v74, v188
	ds_write_b128 v61, v[2:5] offset:49152
	v_cvt_pk_bf16_f32 v2, v0, v43
	v_cvt_pk_bf16_f32 v3, v44, v45
	v_cvt_pk_bf16_f32 v4, v46, v47
	v_cvt_pk_bf16_f32 v5, v48, v49
	ds_write_b128 v61, v[2:5] offset:57344
	v_mov_b64_e32 v[50:51], s[0:1]
	v_ashrrev_i32_e32 v75, 4, v74
	v_lshlrev_b32_e32 v16, 3, v74
	v_and_b32_e32 v0, 0x78, v16
	v_add_u32_e32 v17, 32, v75
	v_mad_i64_i32 v[2:3], s[0:1], v75, s3, v[50:51]
	v_lshlrev_b32_e32 v52, 1, v0
	v_mov_b32_e32 v53, v1
	v_mad_i64_i32 v[4:5], s[0:1], v17, s3, v[50:51]
	v_ashrrev_i32_e32 v72, 3, v74
	v_lshl_add_u64 v[2:3], v[2:3], 0, v[52:53]
	v_lshl_add_u64 v[6:7], v[4:5], 0, v[52:53]
	v_lshlrev_b32_e32 v22, 4, v74
; __device__ __forceinline__ int v_st(int k, int c) { const int kk = (k & ~0xC) | ((k & 4) << 1) | ((k & 8) >> 1); return ((kk >> 3) * 4 + (c >> 5)) * 512 + ((kk & 7) * 32 + (c & 31)) * 2; }
; __device__ __forceinline__ int v_rd_base(int lane) { return ((lane & 3) << 3) | (((lane >> 2) & 3) << 6) | (((lane >> 4) & 1) << 5) | (((lane >> 5) & 1) << 8); }
; #define SWAIT() do { if (SD == 1) asm volatile("s_waitcnt vmcnt(0)" ::: "memory"); else if (DK == 128) asm volatile("s_waitcnt vmcnt(4)" ::: "memory"); else asm volatile("s_waitcnt vmcnt(3)" ::: "memory"); } while (0)
; template <int DK, bool QL>
; __device__ __forceinline__ void qkt(f32x16& p0, f32x16& p1, const bf16* Ks, const bf16x8* qr, const char* ql, int r32, int hi) {
;   p0 = f32x16{}; p1 = f32x16{};
; #pragma unroll
;   for (int d0 = 0; d0 < DK / 16; ++d0) { int cb = (d0 * 16 + hi * 8) * 2;
;     const bf16x8 qv = QL ? *reinterpret_cast<const bf16x8*>(ql + d0 * 1024) : qr[d0];
;     bf16x8 b0 = *reinterpret_cast<const bf16x8*>((const char*)Ks + kswz<DK>(r32, cb));
;     bf16x8 b1 = *reinterpret_cast<const bf16x8*>((const char*)Ks + kswz<DK>(32 + r32, cb));
;     p0 = __builtin_amdgcn_mfma_f32_32x32x16_bf16(b0, qv, p0, 0, 0, 0);
;     p1 = __builtin_amdgcn_mfma_f32_32x32x16_bf16(b1, qv, p1, 0, 0, 0); }
; }
; template <int DK, bool NA, bool QL, int SD> ...
;     ...
;   const bf16* Qw = Qb + (long)(wid * 32 + r32) * LDP + hi * 8;
; #pragma unroll
;   for (int d0 = 0; d0 < DK / 16; ++d0) { const bf16x8 qv = *reinterpret_cast<const bf16x8*>(Qw + d0 * 16); if (QL) *reinterpret_cast<bf16x8*>(ql + d0 * 1024) = qv; else qr[d0] = qv; }
;   const int sr = tid >> 4, sc = (tid & 15) * 8, vst0 = v_st(sr, sc), vst1 = v_st(32 + sr, sc);
;   const int ksr = DK == 128 ? sr : (tid >> 3), ksc = DK == 128 ? sc : (tid & 7) * 8;
;   const int vb0 = (int)(uintptr_t)V_lds + v_rd_base(lane);
;   struct { bf16x8 vs0, vs1, ks0, ks1; } sr_[SD];
;     ...
;   f32x16 pA0, pA1, pB0, pB1; float mnA, mnB, alA, alB; bf16x8 pa0, pa1, pa2, pa3;
;   constexpr int SE = 0, SO = SD - 1;
;   SLOAD(SE, 0); asm volatile("s_waitcnt vmcnt(0)" ::: "memory"); SWRITE(0, SE); __syncthreads();
;   qkt<DK, QL>(pA0, pA1, K_lds, qr, ql, r32, hi); HOOK(pA0, pA1, 0); partialSM(pA0, pA1, m_reg, mnA, alA, C, thrRaw);
;   SLOAD(SO, KVBLK); if (SD == 2) { if (2 < NT) SLOAD(SE, 2 * KVBLK); }
;   SWAIT(); SWRITE(1, SO); __syncthreads();
	global_load_dwordx4 v[2:5], v[2:3], off offset:2048
	s_nop 0
	global_load_dwordx4 v[6:9], v[6:7], off offset:2048
	v_mad_i64_i32 v[10:11], s[0:1], v72, s3, v[50:51]
	v_and_b32_e32 v56, 0x70, v22
	v_mov_b32_e32 v57, v1
	v_ashrrev_i32_e32 v0, 1, v74
	s_movk_i32 s0, 0xffe0
	v_lshl_add_u64 v[10:11], v[10:11], 0, v[56:57]
	v_bfi_b32 v0, s0, v0, v74
	v_readlane_b32 s0, v253, 9
	global_load_dwordx4 v[10:13], v[10:11], off offset:1152
	v_readlane_b32 s1, v253, 10
	v_bfe_u32 v18, v16, 5, 2
	v_and_b32_e32 v19, 3, v75
	v_mov_b64_e32 v[14:15], s[0:1]
	v_mad_i64_i32 v[14:15], s[0:1], v0, s3, v[14:15]
	v_lshrrev_b32_e32 v0, 1, v74
	v_and_b32_e32 v0, 16, v0
	v_lshl_add_u64 v[14:15], v[14:15], 0, v[0:1]
	global_load_dwordx4 v[110:113], v[14:15], off offset:128
	global_load_dwordx4 v[106:109], v[14:15], off offset:160
	global_load_dwordx4 v[102:105], v[14:15], off offset:192
	global_load_dwordx4 v[98:101], v[14:15], off offset:224
	v_add_u32_e32 v84, 64, v75
	v_add_u32_e32 v88, 0x60, v75
	v_add_u32_e32 v92, 64, v72
	v_mad_i64_i32 v[84:85], s[0:1], v84, s3, v[50:51]
	v_mad_i64_i32 v[88:89], s[0:1], v88, s3, v[50:51]
	v_mad_i64_i32 v[92:93], s[0:1], v92, s3, v[50:51]
	v_lshl_add_u64 v[84:85], v[84:85], 0, v[52:53]
	v_lshl_add_u64 v[88:89], v[88:89], 0, v[52:53]
	v_lshl_add_u64 v[92:93], v[92:93], 0, v[56:57]
	global_load_dwordx4 v[84:87], v[84:85], off offset:2048
	global_load_dwordx4 v[88:91], v[88:89], off offset:2048
	global_load_dwordx4 v[92:95], v[92:93], off offset:1152
	v_and_b32_e32 v14, 0xfffff0, v75
	v_lshlrev_b32_e32 v15, 1, v75
	v_and_or_b32 v14, v15, 8, v14
	v_lshrrev_b32_e32 v15, 1, v75
	v_lshrrev_b32_e32 v14, 1, v14
	v_or_b32_e32 v14, v14, v18
	v_and_or_b32 v15, v15, 4, v19
	v_lshlrev_b32_e32 v14, 9, v14
	v_lshlrev_b32_e32 v15, 6, v15
	v_and_b32_e32 v19, 48, v22
	v_and_b32_e32 v20, 0xfffff0, v17
	v_lshlrev_b32_e32 v17, 1, v17
	v_or3_b32 v14, v14, v15, v19
	v_and_or_b32 v17, v17, 8, v20
	v_lshrrev_b32_e32 v17, 1, v17
	v_add_u32_e32 v212, 0, v14
	v_and_b32_e32 v76, 31, v74
	v_or_b32_e32 v17, v17, v18
	s_waitcnt vmcnt(0)
	v_lshlrev_b32_e32 v17, 9, v17
	v_lshlrev_b32_e32 v26, 7, v76
	v_and_b32_e32 v27, 0x70, v16
	v_or3_b32 v15, v17, v15, v19
	v_add_u32_e32 v213, 0, v15
	v_and_b32_e32 v77, 63, v74
	v_lshlrev_b32_e32 v28, 3, v77
	v_and_b32_e32 v22, 0xc0, v22
	v_and_or_b32 v29, v28, 24, v22
	v_lshlrev_b32_e32 v22, 1, v74
	v_and_b32_e32 v30, 32, v22
	v_mad_i64_i32 v[58:59], s[0:1], v75, s3, 0
	v_mad_i64_i32 v[54:55], s[0:1], v72, s3, 0
	s_mov_b32 s15, s13
	s_mov_b32 s1, s13
	s_mov_b32 s16, s13
	s_mov_b32 s17, s13
	s_mov_b32 s18, s13
	s_mov_b32 s19, s13
	s_mov_b32 s20, s13
	s_mov_b32 s21, s13
	s_mov_b32 s22, s13
	s_mov_b32 s23, s13
	s_mov_b32 s24, s13
	s_mov_b32 s25, s13
	s_mov_b32 s26, s13
	s_mov_b32 s27, s13
	v_add_u32_e32 v68, 64, v72
	v_mov_b32_e32 v209, 0
	s_waitcnt vmcnt(6)
	ds_write_b128 v212, v[2:5]
	v_lshlrev_b32_e32 v2, 7, v72
	v_and_b32_e32 v3, 0x70, v74
	v_bitop3_b32 v2, v56, v2, v3 bitop3:0xde
	v_add_u32_e32 v214, 0, v2
	v_bitop3_b32 v2, v0, v26, v27 bitop3:0xde
	v_add_u32_e32 v215, 0, v2
	s_waitcnt vmcnt(5)
	ds_write_b128 v213, v[6:9]
	v_add_u32_e32 v72, 0x80, v72
	s_waitcnt vmcnt(4)
	ds_write_b128 v214, v[10:13] offset:32768
	s_waitcnt lgkmcnt(0)
	s_barrier
	ds_read_b128 v[2:5], v215 offset:32768
	ds_read_b128 v[6:9], v215 offset:36864
	s_waitcnt vmcnt(3) lgkmcnt(1)
	v_mfma_f32_32x32x16_bf16 v[34:49], v[2:5], v[110:113], 0
	v_and_b32_e32 v2, 0x3fffffc0, v74
	v_lshl_add_u32 v207, v2, 2, s8
	v_or_b32_e32 v2, 32, v0
	v_bitop3_b32 v2, v2, v26, v27 bitop3:0xde
	v_add_u32_e32 v216, 0, v2
	ds_read_b128 v[18:21], v216 offset:32768
	ds_read_b128 v[22:25], v216 offset:36864
	s_waitcnt vmcnt(2) lgkmcnt(1)
	v_mfma_f32_32x32x16_bf16 v[34:49], v[18:21], v[106:109], v[34:49]
	v_and_b32_e32 v18, 0x100, v28
	v_or3_b32 v78, v29, v30, v18
	v_or_b32_e32 v18, 64, v0
	v_bitop3_b32 v18, v18, v26, v27 bitop3:0xde
	v_add_u32_e32 v217, 0, v18
	ds_read_b128 v[18:21], v217 offset:32768
	s_mov_b32 s8, 1
	v_mfma_f32_32x32x16_bf16 v[2:17], v[6:9], v[110:113], 0
	v_add_u32_e32 v211, s2, v78
	v_writelane_b32 v254, s0, 62
	v_lshl_add_u32 v208, v76, 2, v207
	s_nop 0
	v_writelane_b32 v255, s2, 0
	v_writelane_b32 v255, s3, 1
	v_writelane_b32 v255, s4, 2
	s_waitcnt lgkmcnt(1)
	v_mfma_f32_32x32x16_bf16 v[2:17], v[22:25], v[106:109], v[2:17]
	ds_read_b128 v[22:25], v217 offset:36864
	v_writelane_b32 v255, s5, 3
	v_writelane_b32 v255, s6, 4
	v_writelane_b32 v255, s7, 5
	v_writelane_b32 v255, s8, 6
	v_writelane_b32 v255, s9, 7
	v_writelane_b32 v255, s10, 8
	s_waitcnt vmcnt(1) lgkmcnt(1)
	v_mfma_f32_32x32x16_bf16 v[34:49], v[18:21], v[102:105], v[34:49]
	v_or_b32_e32 v18, 0x60, v0
	v_bitop3_b32 v18, v18, v26, v27 bitop3:0xde
	v_add_u32_e32 v218, 0, v18
	ds_read_b128 v[18:21], v218 offset:32768
	ds_read_b128 v[60:63], v218 offset:36864
	v_writelane_b32 v255, s11, 9
	v_writelane_b32 v255, s12, 10
	s_waitcnt lgkmcnt(2)
	v_mfma_f32_32x32x16_bf16 v[2:17], v[22:25], v[102:105], v[2:17]
	v_writelane_b32 v255, s13, 11
	v_writelane_b32 v255, s14, 12
	v_writelane_b32 v254, s1, 63
	v_writelane_b32 v255, s15, 13
	v_mad_i64_i32 v[68:69], s[0:1], v68, s3, v[50:51]
	v_lshl_add_u64 v[68:69], v[68:69], 0, v[56:57]
	s_waitcnt vmcnt(0) lgkmcnt(1)
; #define SLOAD(i, k0) do { sr_[i].vs0 = *reinterpret_cast<const bf16x8*>(&Vh[(long)((k0) + sr) * LDP + sc]); sr_[i].vs1 = *reinterpret_cast<const bf16x8*>(&Vh[(long)((k0) + 32 + sr) * LDP + sc]); \
;     sr_[i].ks0 = *reinterpret_cast<const bf16x8*>(&Kh[(long)((k0) + ksr) * LDP + ksc]); if (DK == 128) sr_[i].ks1 = *reinterpret_cast<const bf16x8*>(&Kh[(long)((k0) + 32 + ksr) * LDP + ksc]); } while (0)
; #define SWAIT() do { if (SD == 1) asm volatile("s_waitcnt vmcnt(0)" ::: "memory"); else if (DK == 128) asm volatile("s_waitcnt vmcnt(4)" ::: "memory"); else asm volatile("s_waitcnt vmcnt(3)" ::: "memory"); } while (0)
; #define HOOK(P0, P1, j) do { if (NA) na_hook(P0, P1, krow0 + (j), q_row, q_col, win_r, win_c, rpb, inv_scale, hi); } while (0)
; __device__ __forceinline__ void partialSM(f32x16& p0, f32x16& p1, float& m_reg, float& mn, float& alpha, float C, float thrRaw) {
;   float pmax = p0[0];
; #pragma unroll
;   for (int r = 1; r < 16; ++r) pmax = fmaxf(pmax, p0[r]);
; #pragma unroll
;   for (int r = 0; r < 16; ++r) pmax = fmaxf(pmax, p1[r]);
;   { auto rr = __builtin_amdgcn_permlane32_swap(__float_as_uint(pmax), __float_as_uint(pmax), false, false);
;     pmax = fmaxf(__uint_as_float(rr[0]), __uint_as_float(rr[1])); }
;   if (__builtin_expect(__all(pmax - m_reg <= thrRaw), 1)) { mn = m_reg; alpha = 1.f; }
;   else { mn = fmaxf(m_reg, pmax); alpha = __builtin_amdgcn_exp2f((m_reg - mn) * C); m_reg = mn; }
;   float mnC = -mn * C;
; #pragma unroll
;   for (int r = 0; r < 16; ++r) p0[r] = fmaf(p0[r], C, mnC);
; #pragma unroll
;   for (int r = 0; r < 16; ++r) p1[r] = fmaf(p1[r], C, mnC);
; #pragma unroll
;   for (int r = 0; r < 16; ++r) p0[r] = __builtin_amdgcn_exp2f(p0[r]);
; }
; template <int DK, bool NA, bool QL, int SD> ...
;     ...
;   SLOAD(SE, 0); asm volatile("s_waitcnt vmcnt(0)" ::: "memory"); SWRITE(0, SE); __syncthreads();
;   qkt<DK, QL>(pA0, pA1, K_lds, qr, ql, r32, hi); HOOK(pA0, pA1, 0); partialSM(pA0, pA1, m_reg, mnA, alA, C, thrRaw);
;   SLOAD(SO, KVBLK); if (SD == 2) { if (2 < NT) SLOAD(SE, 2 * KVBLK); }
;   SWAIT(); SWRITE(1, SO); __syncthreads();
	v_mfma_f32_32x32x16_bf16 v[34:49], v[18:21], v[98:101], v[34:49]
	v_mov_b64_e32 v[32:33], s[26:27]
	v_mov_b64_e32 v[18:19], s[12:13]
	v_mov_b64_e32 v[30:31], s[24:25]
	v_mov_b64_e32 v[28:29], s[22:23]
	v_mov_b64_e32 v[26:27], s[20:21]
	v_mov_b64_e32 v[24:25], s[18:19]
	v_mov_b64_e32 v[22:23], s[16:17]
	s_waitcnt lgkmcnt(0)
	v_mfma_f32_32x32x16_bf16 v[2:17], v[60:63], v[98:101], v[2:17]
	s_nop 2
	v_max_f32_e32 v60, v35, v35
	v_max_f32_e32 v61, v34, v34
	v_max_f32_e32 v60, v61, v60
	v_max3_f32 v60, v60, v36, v37
	v_max3_f32 v60, v60, v38, v39
	v_max3_f32 v60, v60, v40, v41
	v_max3_f32 v60, v60, v42, v43
	v_max3_f32 v60, v60, v44, v45
	v_max3_f32 v60, v60, v46, v47
	v_max3_f32 v60, v60, v48, v49
	v_max3_f32 v60, v60, v2, v3
	v_max3_f32 v60, v60, v4, v5
	v_max3_f32 v60, v60, v6, v7
	v_max3_f32 v60, v60, v8, v9
	v_max3_f32 v73, v60, v10, v11
	v_max3_f32 v73, v73, v12, v13
	v_add_u32_e32 v60, 64, v75
	v_add_u32_e32 v62, 0x60, v75
	v_max3_f32 v73, v73, v14, v15
	v_mad_i64_i32 v[60:61], s[0:1], v60, s3, v[50:51]
	v_mad_i64_i32 v[62:63], s[0:1], v62, s3, v[50:51]
	v_max3_f32 v79, v73, v16, v17
	v_mad_i64_i32 v[72:73], s[0:1], v72, s3, v[50:51]
	v_lshl_add_u64 v[60:61], v[60:61], 0, v[52:53]
	v_lshl_add_u64 v[64:65], v[62:63], 0, v[52:53]
	v_lshl_add_u64 v[56:57], v[72:73], 0, v[56:57]
	s_nop 0
	v_add_u32_e32 v72, 0x80, v75
	v_mov_b64_e32 v[20:21], s[14:15]
	global_load_dwordx4 v[122:125], v[56:57], off offset:1152
	v_add_u32_e32 v56, 0xa0, v75
	v_mad_i64_i32 v[56:57], s[0:1], v56, s3, v[50:51]
	v_lshl_add_u64 v[56:57], v[56:57], 0, v[52:53]
	v_mad_i64_i32 v[50:51], s[0:1], v72, s3, v[50:51]
	v_lshl_add_u64 v[50:51], v[50:51], 0, v[52:53]
	global_load_dwordx4 v[118:121], v[56:57], off offset:2048
	global_load_dwordx4 v[114:117], v[50:51], off offset:2048
	v_mov_b32_e32 v50, v79
	s_nop 1
	v_permlane32_swap_b32_e32 v79, v50
	v_max_f32_e32 v50, v50, v50
	v_max_f32_e32 v51, v79, v79
	v_max_f32_e32 v50, v51, v50
	v_add_f32_e32 v51, 0x7149f2ca, v50
	s_mov_b32 s0, 0x42800000
	v_max_f32_e32 v50, 0xf149f2ca, v50
	v_cmp_ge_f32_e32 vcc, s0, v51
	v_sub_f32_e32 v51, 0xf149f2ca, v50
	v_mul_f32_e32 v51, 0x3e38aa3b, v51
	v_exp_f32_e32 v51, v51
	s_cmp_eq_u64 vcc, exec
	s_cselect_b64 vcc, -1, 0
	v_cndmask_b32_e32 v142, v50, v199, vcc
	v_mul_f32_e32 v50, 0xbe38aa3b, v142
	v_cndmask_b32_e64 v219, v51, 1.0, vcc
	v_mov_b32_e32 v51, v50
	v_fmac_f32_e32 v51, 0x3e38aa3b, v49
	s_mov_b32 s0, 0x3e38aa3b
	v_fmamk_f32 v34, v34, 0x3e38aa3b, v50
	v_fmamk_f32 v35, v35, 0x3e38aa3b, v50
	v_fmamk_f32 v36, v36, 0x3e38aa3b, v50
	v_fmamk_f32 v37, v37, 0x3e38aa3b, v50
	v_fmamk_f32 v38, v38, 0x3e38aa3b, v50
	v_fmamk_f32 v39, v39, 0x3e38aa3b, v50
	v_fmamk_f32 v40, v40, 0x3e38aa3b, v50
	v_fmamk_f32 v41, v41, 0x3e38aa3b, v50
	v_fmamk_f32 v42, v42, 0x3e38aa3b, v50
	v_fmamk_f32 v43, v43, 0x3e38aa3b, v50
	v_fmamk_f32 v44, v44, 0x3e38aa3b, v50
	v_fmamk_f32 v45, v45, 0x3e38aa3b, v50
	v_fmamk_f32 v46, v46, 0x3e38aa3b, v50
	v_fmamk_f32 v47, v47, 0x3e38aa3b, v50
	v_fmamk_f32 v48, v48, 0x3e38aa3b, v50
	v_pk_fma_f32 v[138:139], v[2:3], s[0:1], v[50:51] op_sel_hi:[1,0,0]
	s_addk_i32 s2, 0x4000
	v_and_b32_e32 v2, 15, v74
	v_exp_f32_e32 v177, v34
	v_exp_f32_e32 v226, v35
	v_exp_f32_e32 v161, v36
	v_exp_f32_e32 v223, v37
	v_exp_f32_e32 v153, v38
	v_exp_f32_e32 v176, v39
	v_exp_f32_e32 v152, v40
	v_exp_f32_e32 v160, v41
	v_exp_f32_e32 v149, v42
	v_exp_f32_e32 v151, v43
	v_exp_f32_e32 v147, v44
	v_exp_f32_e32 v150, v45
	v_exp_f32_e32 v145, v46
	v_exp_f32_e32 v148, v47
	v_exp_f32_e32 v144, v48
	v_exp_f32_e32 v146, v51
	v_add_u32_e32 v210, s2, v78
	v_lshl_or_b32 v58, v2, 4, v58
	v_readlane_b32 s2, v254, 34
	v_and_b32_e32 v2, 7, v74
	s_waitcnt vmcnt(3)
	v_readlane_b32 s3, v254, 35
	v_lshl_or_b32 v54, v2, 4, v54
	v_pk_fma_f32 v[132:133], v[16:17], s[0:1], v[50:51] op_sel_hi:[1,0,0]
	v_pk_fma_f32 v[134:135], v[14:15], s[0:1], v[50:51] op_sel_hi:[1,0,0]
	v_pk_fma_f32 v[140:141], v[12:13], s[0:1], v[50:51] op_sel_hi:[1,0,0]
	v_pk_fma_f32 v[126:127], v[10:11], s[0:1], v[50:51] op_sel_hi:[1,0,0]
	v_pk_fma_f32 v[128:129], v[8:9], s[0:1], v[50:51] op_sel_hi:[1,0,0]
	v_pk_fma_f32 v[130:131], v[6:7], s[0:1], v[50:51] op_sel_hi:[1,0,0]
	v_pk_fma_f32 v[136:137], v[4:5], s[0:1], v[50:51] op_sel_hi:[1,0,0]
	s_waitcnt vmcnt(5)
	ds_write_b128 v212, v[84:87] offset:16384
	s_waitcnt vmcnt(4)
	ds_write_b128 v213, v[88:91] offset:16384
	s_waitcnt vmcnt(3)
	ds_write_b128 v214, v[92:95] offset:49152
	v_lshl_add_u64 v[156:157], s[2:3], 0, v[58:59]
	v_lshl_add_u64 v[158:159], s[2:3], 0, v[54:55]
	v_mov_b64_e32 v[48:49], v[32:33]
	v_mov_b64_e32 v[64:65], v[32:33]
	v_mov_b64_e32 v[2:3], v[18:19]
	v_cmp_gt_u32_e64 s[0:1], 32, v77
	v_mov_b64_e32 v[46:47], v[30:31]
	v_mov_b64_e32 v[44:45], v[28:29]
	v_mov_b64_e32 v[42:43], v[26:27]
	v_mov_b64_e32 v[40:41], v[24:25]
	v_mov_b64_e32 v[38:39], v[22:23]
	v_mov_b64_e32 v[36:37], v[20:21]
	v_mov_b64_e32 v[34:35], v[18:19]
	v_mov_b64_e32 v[62:63], v[30:31]
	v_mov_b64_e32 v[60:61], v[28:29]
	v_mov_b64_e32 v[58:59], v[26:27]
	v_mov_b64_e32 v[56:57], v[24:25]
	v_mov_b64_e32 v[54:55], v[22:23]
	v_mov_b64_e32 v[52:53], v[20:21]
	v_mov_b64_e32 v[50:51], v[18:19]
	v_mov_b64_e32 v[4:5], v[20:21]
	v_mov_b64_e32 v[6:7], v[22:23]
	v_mov_b64_e32 v[8:9], v[24:25]
	v_mov_b64_e32 v[10:11], v[26:27]
	v_mov_b64_e32 v[12:13], v[28:29]
	v_mov_b64_e32 v[14:15], v[30:31]
	v_mov_b64_e32 v[16:17], v[32:33]
	s_waitcnt lgkmcnt(0)
	s_barrier
